# G2 stagger step raised to s_sleep 60 (about 1.8 us) per group
# speedup vs baseline: 1.0021x; 1.0003x over previous
.Lg2stag_loop:
	s_sleep 60
	s_sub_u32 s98, s98, 1
	s_cmp_lg_u32 s98, 0
	s_cbranch_scc1 .Lg2stag_loop
